# f32 source loads of the conversion phase (x, p, weights) use nt policy; plus chained MFMA order, 64-bit clears, p-loop pipeline, DPP row sums
# speedup vs baseline: 1.0049x; 1.0049x over previous
.LBB0_576:
	s_mov_b32 s36, s72
	s_mov_b32 s38, s76
	s_mov_b32 s2, s85
	s_cmp_lg_u32 s2, 0
	s_cselect_b64 s[4:5], -1, 0
	s_cmpk_eq_i32 s38, 0x100
	s_cselect_b64 s[6:7], -1, 0
	s_and_b64 s[4:5], s[4:5], s[6:7]
	s_and_b64 s[4:5], s[4:5], exec
	s_cselect_b32 s40, 0x80, 0
	s_mov_b64 s[0:1], s[74:75]
	s_cmp_lt_i32 s36, s40
	s_cbranch_scc1 .LBB0_888
	s_cmp_lg_u32 s2, 0
	s_cselect_b64 s[24:25], -1, 0
	s_cmp_gt_i32 s2, 8
	s_cselect_b32 s3, -9, 0
	s_cselect_b32 s6, 3, 1
	s_add_i32 s3, s3, s2
	s_cmp_gt_i32 s3, 4
	s_cselect_b64 s[4:5], -1, 0
	s_cmp_lg_u64 s[4:5], 0
	s_addc_u32 s4, s6, 0
	s_cmp_eq_u32 s2, 0
	v_mov_b32_e32 v64, v242
	s_cselect_b64 s[8:9], -1, 0
	s_load_dwordx2 s[6:7], s[0:1], 0xd0
	s_and_b64 s[2:3], s[8:9], exec
	s_cselect_b32 s22, 0, s4
	s_sub_i32 s2, s36, s40
	s_sub_i32 s14, s38, s40
	s_lshl_b32 s2, s2, 3
	s_mov_b32 s20, 0
	s_add_i32 s26, s2, s73
	s_lshl_b32 s28, s14, 3
	s_mov_b64 s[2:3], -1
	s_and_b64 vcc, exec, s[24:25]
	s_mov_b32 s23, 0
	s_cbranch_vccnz .LBB0_587
	s_cmpk_gt_i32 s26, 0x1fff
	s_cbranch_scc1 .LBB0_583
	s_load_dwordx2 s[12:13], s[0:1], 0x0
	s_ashr_i32 s27, s26, 31
	s_lshl_b64 s[2:3], s[26:27], 13
	v_ashrrev_i32_e32 v65, 31, v64
	s_waitcnt vmcnt(0)
	v_lshlrev_b64 v[0:1], 4, v[64:65]
	s_waitcnt lgkmcnt(0)
	s_add_u32 s2, s12, s2
	s_addc_u32 s3, s13, s3
	v_lshl_add_u64 v[2:3], s[2:3], 0, v[0:1]
	s_movk_i32 s2, 0x1000
	global_load_dwordx4 v[60:63], v[2:3], off nt
	global_load_dwordx4 v[56:59], v[2:3], off offset:1024 nt
	global_load_dwordx4 v[52:55], v[2:3], off offset:2048 nt
	global_load_dwordx4 v[44:47], v[2:3], off offset:3072 nt
	v_add_co_u32_e32 v2, vcc, s2, v2
	s_lshl_b64 s[4:5], s[26:27], 8
	s_nop 0
	v_addc_co_u32_e32 v3, vcc, 0, v3, vcc
	global_load_dwordx4 v[48:51], v[2:3], off nt
	global_load_dwordx4 v[40:43], v[2:3], off offset:1024 nt
	global_load_dwordx4 v[36:39], v[2:3], off offset:2048 nt
	global_load_dwordx4 v[32:35], v[2:3], off offset:3072 nt
	s_add_u32 s4, s4, 0x1fb00000
	s_addc_u32 s5, s5, 0
	s_lshl_b32 s15, s36, 3
	s_lshl_b32 s21, s38, 3
	s_add_i32 s15, s73, s15
	s_lshl_b32 s23, s40, 4
	s_add_i32 s16, s15, s21
	s_sub_i32 s16, s16, s23
	s_ashr_i32 s29, s28, 31
	s_lshl_b64 s[10:11], s[26:27], 12
	s_ashr_i32 s17, s16, 31
	v_lshl_add_u64 v[66:67], v[64:65], 2, s[4:5]
	s_lshl_b64 s[4:5], s[28:29], 8
	v_lshl_add_u64 v[68:69], v[64:65], 3, s[10:11]
	s_lshl_b64 s[10:11], s[28:29], 12
	s_lshl_b64 s[16:17], s[16:17], 13
	s_add_u32 s18, s12, s16
	s_addc_u32 s19, s13, s17
	v_lshl_add_u64 v[0:1], s[18:19], 0, v[0:1]
	s_mov_b64 s[18:19], 0x1c00
	s_lshl_b32 s17, s40, 3
	v_lshl_add_u64 v[70:71], v[0:1], 0, s[18:19]
	v_cmp_eq_u32_e64 s[2:3], 0, v64
	s_lshl_b64 s[12:13], s[28:29], 13
	s_sub_i32 s16, s21, s23
	s_sub_i32 s17, 0, s17
	s_waitcnt vmcnt(7)
	v_mov_b64_e32 v[0:1], v[60:61]
	s_waitcnt vmcnt(6)
	v_mov_b64_e32 v[4:5], v[56:57]
	s_waitcnt vmcnt(5)
	v_mov_b64_e32 v[8:9], v[52:53]
	s_waitcnt vmcnt(4)
	v_mov_b64_e32 v[12:13], v[44:45]
	v_mov_b64_e32 v[2:3], v[62:63]
	v_mov_b64_e32 v[6:7], v[58:59]
	s_waitcnt vmcnt(3)
	v_mov_b64_e32 v[16:17], v[48:49]
	s_waitcnt vmcnt(2)
	v_mov_b64_e32 v[20:21], v[40:41]
	s_waitcnt vmcnt(1)
	v_mov_b64_e32 v[24:25], v[36:37]
	s_waitcnt vmcnt(0)
	v_mov_b64_e32 v[28:29], v[32:33]
	v_mov_b64_e32 v[10:11], v[54:55]
	v_mov_b64_e32 v[14:15], v[46:47]
	v_mov_b64_e32 v[18:19], v[50:51]
	v_mov_b64_e32 v[22:23], v[42:43]
	v_mov_b64_e32 v[26:27], v[38:39]
	v_mov_b64_e32 v[30:31], v[34:35]
	s_branch .LBB0_581

.LBB0_581:
	s_add_i32 s18, s16, s15
	s_cmpk_gt_i32 s18, 0x1fff
	s_cbranch_scc1 .LBB0_580
	v_add_co_u32_e32 v8, vcc, 0xfffff000, v70
	s_nop 1
	v_addc_co_u32_e32 v9, vcc, -1, v71, vcc
	global_load_dwordx4 v[0:3], v[8:9], off offset:-3072 nt
	global_load_dwordx4 v[4:7], v[8:9], off offset:-2048 nt
	s_nop 0
	global_load_dwordx4 v[8:11], v[8:9], off offset:-1024 nt
	s_nop 0
	global_load_dwordx4 v[12:15], v[70:71], off offset:-4096 nt
	global_load_dwordx4 v[16:19], v[70:71], off offset:-3072 nt
	global_load_dwordx4 v[20:23], v[70:71], off offset:-2048 nt
	global_load_dwordx4 v[24:27], v[70:71], off offset:-1024 nt
	global_load_dwordx4 v[28:31], v[70:71], off nt
	s_branch .LBB0_580

.LBB0_585:
	global_load_dwordx4 v[6:9], v[4:5], off nt
	v_lshl_add_u64 v[48:49], v[4:5], 0, s[12:13]
	s_mov_b32 s14, 1
	s_add_i32 s5, s15, s4
	s_cmp_lt_i32 s5, 0x100000
	s_cbranch_scc0 .Lp_ld_done
	global_load_dwordx4 v[10:13], v[48:49], off nt
	v_lshl_add_u64 v[48:49], v[48:49], 0, s[12:13]
	s_mov_b32 s14, 2
	s_add_i32 s5, s5, s4
	s_cmp_lt_i32 s5, 0x100000
	s_cbranch_scc0 .Lp_ld_done
	global_load_dwordx4 v[14:17], v[48:49], off nt
	v_lshl_add_u64 v[48:49], v[48:49], 0, s[12:13]
	s_mov_b32 s14, 3
	s_add_i32 s5, s5, s4
	s_cmp_lt_i32 s5, 0x100000
	s_cbranch_scc0 .Lp_ld_done
	global_load_dwordx4 v[18:21], v[48:49], off nt
	v_lshl_add_u64 v[48:49], v[48:49], 0, s[12:13]
	s_mov_b32 s14, 4
	s_add_i32 s5, s5, s4

.LBB0_720:
	s_lshr_b32 s12, s39, 6
	v_cvt_f32_u32_e32 v0, s12
	s_sub_i32 s15, 0, s12
	s_abs_i32 s14, s27
	s_ashr_i32 s13, s27, 31
	v_rcp_iflag_f32_e32 v0, v0
	v_ashrrev_i32_e32 v1, 4, v64
	v_mul_f32_e32 v0, 0x4f7ffffe, v0
	v_cvt_u32_f32_e32 v0, v0
	s_nop 0
	v_readfirstlane_b32 s16, v0
	s_mul_i32 s15, s15, s16
	s_mul_hi_u32 s15, s16, s15
	s_add_i32 s16, s16, s15
	s_mul_hi_u32 s15, s14, s16
	s_mul_i32 s16, s15, s12
	s_sub_i32 s14, s14, s16
	s_add_i32 s17, s15, 1
	s_sub_i32 s16, s14, s12
	s_cmp_ge_u32 s14, s12
	s_cselect_b32 s15, s17, s15
	s_cselect_b32 s14, s16, s14
	s_add_i32 s16, s15, 1
	s_cmp_ge_u32 s14, s12
	s_cselect_b32 s14, s16, s15
	s_xor_b32 s14, s14, s13
	s_sub_i32 s13, s14, s13
	v_lshl_add_u32 v4, s13, 6, v1
	v_ashrrev_i32_e32 v0, 31, v4
	v_mul_lo_u32 v2, s10, v0
	v_mul_lo_u32 v3, s11, v4
	v_mad_u64_u32 v[0:1], s[14:15], s10, v4, 0
	s_mul_i32 s12, s13, s12
	v_add3_u32 v1, v1, v2, v3
	v_lshlrev_b32_e32 v2, 4, v64
	s_sub_i32 s12, s27, s12
	v_and_b32_e32 v184, 0xf0, v2
	v_add_u32_e32 v2, 4, v4
	s_lshl_b32 s12, s12, 6
	v_ashrrev_i32_e32 v3, 31, v2
	s_ashr_i32 s13, s12, 31
	v_mul_lo_u32 v5, s10, v3
	v_mul_lo_u32 v6, s11, v2
	v_mad_u64_u32 v[2:3], s[14:15], s10, v2, 0
	v_lshl_add_u64 v[0:1], v[0:1], 2, s[8:9]
	s_lshl_b64 s[12:13], s[12:13], 2
	v_add3_u32 v3, v3, v5, v6
	v_lshl_add_u64 v[0:1], v[0:1], 0, s[12:13]
	v_lshl_add_u64 v[2:3], v[2:3], 2, s[8:9]
	v_lshl_add_u64 v[0:1], v[0:1], 0, v[184:185]
	v_lshl_add_u64 v[2:3], v[2:3], 0, s[12:13]
	v_lshl_add_u64 v[2:3], v[2:3], 0, v[184:185]
	global_load_dwordx4 v[120:123], v[0:1], off nt
	global_load_dwordx4 v[124:127], v[2:3], off nt
	v_add_u32_e32 v0, 8, v4
	v_ashrrev_i32_e32 v1, 31, v0
	v_mul_lo_u32 v2, s10, v1
	v_mul_lo_u32 v3, s11, v0
	v_mad_u64_u32 v[0:1], s[14:15], s10, v0, 0
	v_add3_u32 v1, v1, v2, v3
	v_add_u32_e32 v2, 12, v4
	v_ashrrev_i32_e32 v3, 31, v2
	v_mul_lo_u32 v5, s10, v3
	v_mul_lo_u32 v6, s11, v2
	v_mad_u64_u32 v[2:3], s[14:15], s10, v2, 0
	v_lshl_add_u64 v[0:1], v[0:1], 2, s[8:9]
	v_add3_u32 v3, v3, v5, v6
	v_lshl_add_u64 v[0:1], v[0:1], 0, s[12:13]
	v_lshl_add_u64 v[2:3], v[2:3], 2, s[8:9]
	v_lshl_add_u64 v[0:1], v[0:1], 0, v[184:185]
	v_lshl_add_u64 v[2:3], v[2:3], 0, s[12:13]
	v_lshl_add_u64 v[2:3], v[2:3], 0, v[184:185]
	global_load_dwordx4 v[116:119], v[0:1], off nt
	global_load_dwordx4 v[112:115], v[2:3], off nt
	v_add_u32_e32 v0, 16, v4
	v_ashrrev_i32_e32 v1, 31, v0
	v_mul_lo_u32 v2, s10, v1
	v_mul_lo_u32 v3, s11, v0
	v_mad_u64_u32 v[0:1], s[14:15], s10, v0, 0
	v_add3_u32 v1, v1, v2, v3
	v_add_u32_e32 v2, 20, v4
	v_ashrrev_i32_e32 v3, 31, v2
	v_mul_lo_u32 v5, s10, v3
	v_mul_lo_u32 v6, s11, v2
	v_mad_u64_u32 v[2:3], s[14:15], s10, v2, 0
	v_lshl_add_u64 v[0:1], v[0:1], 2, s[8:9]
	v_add3_u32 v3, v3, v5, v6
	v_lshl_add_u64 v[0:1], v[0:1], 0, s[12:13]
	v_lshl_add_u64 v[2:3], v[2:3], 2, s[8:9]
	v_lshl_add_u64 v[0:1], v[0:1], 0, v[184:185]
	v_lshl_add_u64 v[2:3], v[2:3], 0, s[12:13]
	v_lshl_add_u64 v[2:3], v[2:3], 0, v[184:185]
	global_load_dwordx4 v[104:107], v[0:1], off nt
	global_load_dwordx4 v[108:111], v[2:3], off nt
	v_add_u32_e32 v0, 24, v4
	v_ashrrev_i32_e32 v1, 31, v0
	v_mul_lo_u32 v2, s10, v1
	v_mul_lo_u32 v3, s11, v0
	v_mad_u64_u32 v[0:1], s[14:15], s10, v0, 0
	v_add3_u32 v1, v1, v2, v3
	v_add_u32_e32 v2, 28, v4
	v_ashrrev_i32_e32 v3, 31, v2
	v_mul_lo_u32 v5, s10, v3
	v_mul_lo_u32 v6, s11, v2
	v_mad_u64_u32 v[2:3], s[14:15], s10, v2, 0
	v_lshl_add_u64 v[0:1], v[0:1], 2, s[8:9]
	v_add3_u32 v3, v3, v5, v6
	v_lshl_add_u64 v[0:1], v[0:1], 0, s[12:13]
	v_lshl_add_u64 v[2:3], v[2:3], 2, s[8:9]
	v_lshl_add_u64 v[0:1], v[0:1], 0, v[184:185]
	v_lshl_add_u64 v[2:3], v[2:3], 0, s[12:13]
	v_lshl_add_u64 v[2:3], v[2:3], 0, v[184:185]
	global_load_dwordx4 v[80:83], v[0:1], off nt
	global_load_dwordx4 v[84:87], v[2:3], off nt
	v_add_u32_e32 v0, 32, v4
	v_ashrrev_i32_e32 v1, 31, v0
	v_mul_lo_u32 v2, s10, v1
	v_mul_lo_u32 v3, s11, v0
	v_mad_u64_u32 v[0:1], s[14:15], s10, v0, 0
	v_add3_u32 v1, v1, v2, v3
	v_add_u32_e32 v2, 36, v4
	v_ashrrev_i32_e32 v3, 31, v2
	v_mul_lo_u32 v5, s10, v3
	v_mul_lo_u32 v6, s11, v2
	v_mad_u64_u32 v[2:3], s[14:15], s10, v2, 0
	v_lshl_add_u64 v[0:1], v[0:1], 2, s[8:9]
	v_add3_u32 v3, v3, v5, v6
	v_lshl_add_u64 v[0:1], v[0:1], 0, s[12:13]
	v_lshl_add_u64 v[2:3], v[2:3], 2, s[8:9]
	v_lshl_add_u64 v[0:1], v[0:1], 0, v[184:185]
	v_lshl_add_u64 v[2:3], v[2:3], 0, s[12:13]
	v_lshl_add_u64 v[2:3], v[2:3], 0, v[184:185]
	global_load_dwordx4 v[48:51], v[0:1], off nt
	global_load_dwordx4 v[52:55], v[2:3], off nt
	v_add_u32_e32 v0, 40, v4
	v_ashrrev_i32_e32 v1, 31, v0
	v_mul_lo_u32 v2, s10, v1
	v_mul_lo_u32 v3, s11, v0
	v_mad_u64_u32 v[0:1], s[14:15], s10, v0, 0
	v_add3_u32 v1, v1, v2, v3
	v_add_u32_e32 v2, 44, v4
	v_ashrrev_i32_e32 v3, 31, v2
	v_mul_lo_u32 v5, s10, v3
	v_mul_lo_u32 v6, s11, v2
	v_mad_u64_u32 v[2:3], s[14:15], s10, v2, 0
	v_lshl_add_u64 v[0:1], v[0:1], 2, s[8:9]
	v_add3_u32 v3, v3, v5, v6
	v_lshl_add_u64 v[0:1], v[0:1], 0, s[12:13]
	v_lshl_add_u64 v[2:3], v[2:3], 2, s[8:9]
	v_lshl_add_u64 v[0:1], v[0:1], 0, v[184:185]
	v_lshl_add_u64 v[2:3], v[2:3], 0, s[12:13]
	v_lshl_add_u64 v[2:3], v[2:3], 0, v[184:185]
	global_load_dwordx4 v[16:19], v[0:1], off nt
	global_load_dwordx4 v[20:23], v[2:3], off nt
	v_add_u32_e32 v0, 48, v4
	v_ashrrev_i32_e32 v1, 31, v0
	v_mul_lo_u32 v2, s10, v1
	v_mul_lo_u32 v3, s11, v0
	v_mad_u64_u32 v[0:1], s[14:15], s10, v0, 0
	v_add3_u32 v1, v1, v2, v3
	v_add_u32_e32 v2, 52, v4
	v_ashrrev_i32_e32 v3, 31, v2
	v_mul_lo_u32 v5, s10, v3
	v_mul_lo_u32 v6, s11, v2
	v_mad_u64_u32 v[2:3], s[14:15], s10, v2, 0
	v_lshl_add_u64 v[0:1], v[0:1], 2, s[8:9]
	v_add3_u32 v3, v3, v5, v6
	v_lshl_add_u64 v[0:1], v[0:1], 0, s[12:13]
	v_lshl_add_u64 v[2:3], v[2:3], 2, s[8:9]
	v_lshl_add_u64 v[0:1], v[0:1], 0, v[184:185]
	v_lshl_add_u64 v[2:3], v[2:3], 0, s[12:13]
	v_lshl_add_u64 v[2:3], v[2:3], 0, v[184:185]
	global_load_dwordx4 v[8:11], v[0:1], off nt
	global_load_dwordx4 v[12:15], v[2:3], off nt
	v_add_u32_e32 v0, 56, v4
	v_ashrrev_i32_e32 v1, 31, v0
	v_mul_lo_u32 v2, s10, v1
	v_mul_lo_u32 v3, s11, v0
	v_mad_u64_u32 v[0:1], s[14:15], s10, v0, 0
	v_add3_u32 v1, v1, v2, v3
	v_add_u32_e32 v2, 60, v4
	v_ashrrev_i32_e32 v3, 31, v2
	v_mul_lo_u32 v4, s10, v3
	v_mul_lo_u32 v5, s11, v2
	v_mad_u64_u32 v[2:3], s[10:11], s10, v2, 0
	v_add3_u32 v3, v3, v4, v5
	v_lshl_add_u64 v[0:1], v[0:1], 2, s[8:9]
	v_lshl_add_u64 v[2:3], v[2:3], 2, s[8:9]
	v_lshl_add_u64 v[0:1], v[0:1], 0, s[12:13]
	v_lshl_add_u64 v[2:3], v[2:3], 0, s[12:13]
	v_lshl_add_u64 v[0:1], v[0:1], 0, v[184:185]
	v_lshl_add_u64 v[4:5], v[2:3], 0, v[184:185]
	global_load_dwordx4 v[0:3], v[0:1], off nt
	s_nop 0
	global_load_dwordx4 v[4:7], v[4:5], off nt

.LBB0_793:
	s_lshr_b32 s10, s36, 6
	v_cvt_f32_u32_e32 v24, s10
	s_sub_i32 s76, 0, s10
	s_abs_i32 s37, s40
	s_ashr_i32 s11, s40, 31
	v_rcp_iflag_f32_e32 v24, v24
	v_mov_b32_e32 v135, v185
	v_mul_f32_e32 v24, 0x4f7ffffe, v24
	v_cvt_u32_f32_e32 v24, v24
	s_nop 0
	v_readfirstlane_b32 s77, v24
	s_mul_i32 s76, s76, s77
	s_mul_hi_u32 s76, s77, s76
	s_add_i32 s77, s77, s76
	s_mul_hi_u32 s76, s37, s77
	s_mul_i32 s77, s76, s10
	s_sub_i32 s37, s37, s77
	s_add_i32 s78, s76, 1
	s_sub_i32 s77, s37, s10
	s_cmp_ge_u32 s37, s10
	s_cselect_b32 s76, s78, s76
	s_cselect_b32 s37, s77, s37
	s_add_i32 s77, s76, 1
	s_cmp_ge_u32 s37, s10
	s_cselect_b32 s37, s77, s76
	s_xor_b32 s37, s37, s11
	s_sub_i32 s11, s37, s11
	v_lshl_add_u32 v98, s11, 6, v132
	v_add_u32_e32 v32, 8, v98
	v_add_u32_e32 v40, 16, v98
	v_add_u32_e32 v56, 24, v98
	v_add_u32_e32 v64, 32, v98
	v_add_u32_e32 v72, 40, v98
	v_add_u32_e32 v88, 48, v98
	v_ashrrev_i32_e32 v24, 31, v98
	v_ashrrev_i32_e32 v33, 31, v32
	v_ashrrev_i32_e32 v41, 31, v40
	v_ashrrev_i32_e32 v57, 31, v56
	v_ashrrev_i32_e32 v65, 31, v64
	v_ashrrev_i32_e32 v73, 31, v72
	v_ashrrev_i32_e32 v89, 31, v88
	v_add_u32_e32 v96, 56, v98
	v_mul_lo_u32 v26, s9, v98
	v_mul_lo_u32 v27, s8, v24
	v_mad_u64_u32 v[24:25], s[76:77], s8, v98, 0
	v_mul_lo_u32 v34, s8, v33
	v_mul_lo_u32 v35, s9, v32
	v_mad_u64_u32 v[32:33], s[76:77], s8, v32, 0
	v_mul_lo_u32 v42, s8, v41
	v_mul_lo_u32 v43, s9, v40
	v_mad_u64_u32 v[40:41], s[76:77], s8, v40, 0
	v_mul_lo_u32 v58, s8, v57
	v_mul_lo_u32 v59, s9, v56
	v_mad_u64_u32 v[56:57], s[76:77], s8, v56, 0
	v_mul_lo_u32 v66, s8, v65
	v_mul_lo_u32 v67, s9, v64
	v_mad_u64_u32 v[64:65], s[76:77], s8, v64, 0
	v_mul_lo_u32 v74, s8, v73
	v_mul_lo_u32 v75, s9, v72
	v_mad_u64_u32 v[72:73], s[76:77], s8, v72, 0
	v_mul_lo_u32 v90, s8, v89
	v_mul_lo_u32 v91, s9, v88
	v_mad_u64_u32 v[88:89], s[76:77], s8, v88, 0
	v_ashrrev_i32_e32 v97, 31, v96
	s_mul_i32 s10, s11, s10
	v_add3_u32 v25, v25, v27, v26
	v_add_u32_e32 v26, 4, v98
	v_add3_u32 v33, v33, v34, v35
	v_add_u32_e32 v34, 12, v98
	v_add3_u32 v41, v41, v42, v43
	v_add_u32_e32 v42, 20, v98
	v_add3_u32 v57, v57, v58, v59
	v_add_u32_e32 v58, 28, v98
	v_add3_u32 v65, v65, v66, v67
	v_add_u32_e32 v66, 36, v98
	v_add3_u32 v73, v73, v74, v75
	v_add_u32_e32 v74, 44, v98
	v_add3_u32 v89, v89, v90, v91
	v_add_u32_e32 v90, 52, v98
	v_mul_lo_u32 v99, s8, v97
	v_mul_lo_u32 v100, s9, v96
	v_mad_u64_u32 v[96:97], s[76:77], s8, v96, 0
	v_add_u32_e32 v98, 60, v98
	s_sub_i32 s10, s40, s10
	v_ashrrev_i32_e32 v27, 31, v26
	v_ashrrev_i32_e32 v35, 31, v34
	v_ashrrev_i32_e32 v43, 31, v42
	v_ashrrev_i32_e32 v59, 31, v58
	v_ashrrev_i32_e32 v67, 31, v66
	v_ashrrev_i32_e32 v75, 31, v74
	v_ashrrev_i32_e32 v91, 31, v90
	v_add3_u32 v97, v97, v99, v100
	v_ashrrev_i32_e32 v99, 31, v98
	s_lshl_b32 s10, s10, 6
	v_mul_lo_u32 v28, s8, v27
	v_mul_lo_u32 v29, s9, v26
	v_mad_u64_u32 v[26:27], s[76:77], s8, v26, 0
	v_mul_lo_u32 v36, s8, v35
	v_mul_lo_u32 v37, s9, v34
	v_mad_u64_u32 v[34:35], s[76:77], s8, v34, 0
	v_mul_lo_u32 v44, s8, v43
	v_mul_lo_u32 v45, s9, v42
	v_mad_u64_u32 v[42:43], s[76:77], s8, v42, 0
	v_mul_lo_u32 v60, s8, v59
	v_mul_lo_u32 v61, s9, v58
	v_mad_u64_u32 v[58:59], s[76:77], s8, v58, 0
	v_mul_lo_u32 v68, s8, v67
	v_mul_lo_u32 v69, s9, v66
	v_mad_u64_u32 v[66:67], s[76:77], s8, v66, 0
	v_mul_lo_u32 v76, s8, v75
	v_mul_lo_u32 v77, s9, v74
	v_mad_u64_u32 v[74:75], s[76:77], s8, v74, 0
	v_mul_lo_u32 v92, s8, v91
	v_mul_lo_u32 v93, s9, v90
	v_mad_u64_u32 v[90:91], s[76:77], s8, v90, 0
	v_mul_lo_u32 v100, s8, v99
	v_mul_lo_u32 v101, s9, v98
	v_mad_u64_u32 v[98:99], s[8:9], s8, v98, 0
	s_ashr_i32 s11, s10, 31
	v_add3_u32 v27, v27, v28, v29
	v_add3_u32 v35, v35, v36, v37
	v_add3_u32 v43, v43, v44, v45
	v_add3_u32 v59, v59, v60, v61
	v_add3_u32 v67, v67, v68, v69
	v_add3_u32 v75, v75, v76, v77
	v_add3_u32 v91, v91, v92, v93
	v_add3_u32 v99, v99, v100, v101
	v_lshl_add_u64 v[24:25], v[24:25], 2, s[4:5]
	s_lshl_b64 s[10:11], s[10:11], 2
	v_lshl_add_u64 v[26:27], v[26:27], 2, s[4:5]
	v_lshl_add_u64 v[32:33], v[32:33], 2, s[4:5]
	v_lshl_add_u64 v[34:35], v[34:35], 2, s[4:5]
	v_lshl_add_u64 v[40:41], v[40:41], 2, s[4:5]
	v_lshl_add_u64 v[42:43], v[42:43], 2, s[4:5]
	v_lshl_add_u64 v[56:57], v[56:57], 2, s[4:5]
	v_lshl_add_u64 v[58:59], v[58:59], 2, s[4:5]
	v_lshl_add_u64 v[64:65], v[64:65], 2, s[4:5]
	v_lshl_add_u64 v[66:67], v[66:67], 2, s[4:5]
	v_lshl_add_u64 v[72:73], v[72:73], 2, s[4:5]
	v_lshl_add_u64 v[74:75], v[74:75], 2, s[4:5]
	v_lshl_add_u64 v[88:89], v[88:89], 2, s[4:5]
	v_lshl_add_u64 v[90:91], v[90:91], 2, s[4:5]
	v_lshl_add_u64 v[96:97], v[96:97], 2, s[4:5]
	v_lshl_add_u64 v[98:99], v[98:99], 2, s[4:5]
	v_lshl_add_u64 v[24:25], v[24:25], 0, s[10:11]
	v_lshl_add_u64 v[26:27], v[26:27], 0, s[10:11]
	v_lshl_add_u64 v[32:33], v[32:33], 0, s[10:11]
	v_lshl_add_u64 v[34:35], v[34:35], 0, s[10:11]
	v_lshl_add_u64 v[40:41], v[40:41], 0, s[10:11]
	v_lshl_add_u64 v[42:43], v[42:43], 0, s[10:11]
	v_lshl_add_u64 v[56:57], v[56:57], 0, s[10:11]
	v_lshl_add_u64 v[58:59], v[58:59], 0, s[10:11]
	v_lshl_add_u64 v[64:65], v[64:65], 0, s[10:11]
	v_lshl_add_u64 v[66:67], v[66:67], 0, s[10:11]
	v_lshl_add_u64 v[72:73], v[72:73], 0, s[10:11]
	v_lshl_add_u64 v[74:75], v[74:75], 0, s[10:11]
	v_lshl_add_u64 v[88:89], v[88:89], 0, s[10:11]
	v_lshl_add_u64 v[90:91], v[90:91], 0, s[10:11]
	v_lshl_add_u64 v[96:97], v[96:97], 0, s[10:11]
	v_lshl_add_u64 v[98:99], v[98:99], 0, s[10:11]
	v_lshl_add_u64 v[24:25], v[24:25], 0, v[134:135]
	v_lshl_add_u64 v[28:29], v[26:27], 0, v[134:135]
	v_lshl_add_u64 v[32:33], v[32:33], 0, v[134:135]
	v_lshl_add_u64 v[36:37], v[34:35], 0, v[134:135]
	v_lshl_add_u64 v[40:41], v[40:41], 0, v[134:135]
	v_lshl_add_u64 v[44:45], v[42:43], 0, v[134:135]
	v_lshl_add_u64 v[56:57], v[56:57], 0, v[134:135]
	v_lshl_add_u64 v[60:61], v[58:59], 0, v[134:135]
	v_lshl_add_u64 v[64:65], v[64:65], 0, v[134:135]
	v_lshl_add_u64 v[68:69], v[66:67], 0, v[134:135]
	v_lshl_add_u64 v[72:73], v[72:73], 0, v[134:135]
	v_lshl_add_u64 v[76:77], v[74:75], 0, v[134:135]
	v_lshl_add_u64 v[88:89], v[88:89], 0, v[134:135]
	v_lshl_add_u64 v[92:93], v[90:91], 0, v[134:135]
	v_lshl_add_u64 v[96:97], v[96:97], 0, v[134:135]
	v_lshl_add_u64 v[100:101], v[98:99], 0, v[134:135]
	global_load_dwordx4 v[24:27], v[24:25], off nt
	s_nop 0
	global_load_dwordx4 v[28:31], v[28:29], off nt
	s_nop 0
	global_load_dwordx4 v[32:35], v[32:33], off nt
	s_nop 0
	global_load_dwordx4 v[36:39], v[36:37], off nt
	s_nop 0
	global_load_dwordx4 v[40:43], v[40:41], off nt
	s_nop 0
	global_load_dwordx4 v[44:47], v[44:45], off nt
	s_nop 0
	global_load_dwordx4 v[56:59], v[56:57], off nt
	s_nop 0
	global_load_dwordx4 v[60:63], v[60:61], off nt
	s_nop 0
	global_load_dwordx4 v[64:67], v[64:65], off nt
	s_nop 0
	global_load_dwordx4 v[68:71], v[68:69], off nt
	s_nop 0
	global_load_dwordx4 v[72:75], v[72:73], off nt
	s_nop 0
	global_load_dwordx4 v[76:79], v[76:77], off nt
	s_nop 0
	global_load_dwordx4 v[88:91], v[88:89], off nt
	s_nop 0
	global_load_dwordx4 v[92:95], v[92:93], off nt
	s_nop 0
	global_load_dwordx4 v[96:99], v[96:97], off nt
	s_nop 0
	global_load_dwordx4 v[100:103], v[100:101], off nt
